# v_m10 + inproj: tile index remapped XCD-contiguously (each XCD works through 8.5 consecutive row-blocks)
# speedup vs baseline: 1.0120x; 1.0019x over previous
; DI void gemm_core256(f32x16 (&acc)[4][2], const u16* __restrict__ A, int lda, const u16* __restrict__ W, int ldw, int K,
;                      u16* sA, u16* sW) {
;     ...
;   const unsigned aoff = (unsigned)(lr * lda + lc * 8);
;   const unsigned woff = (unsigned)(lr * ldw + lc * 8);
;   u32x4 ra[8], rw[4];
; #pragma unroll
;   for (int i = 0; i < 8; i++) {
;     ra[i] = *(const u32x4*)(A + (aoff + (unsigned)(i * 32 * lda)));
;     if (i < 4) rw[i] = *(const u32x4*)(W + (woff + (unsigned)(i * 32 * ldw)));
;   }
; DI void phase_inproj(const Params& p, int l, int half, char* smem) {
;     ...
;   for (int it = blockIdx.x; it < ntiles; it += gridDim.x) {
;     int tm = it / 30, tn = it % 30;
;     f32x16 acc[4][2];
; #pragma unroll
;     for (int a = 0; a < 4; a++)
; #pragma unroll
;       for (int b = 0; b < 2; b++)
; #pragma unroll
;         for (int i = 0; i < 16; i++) acc[a][b][i] = 0.f;
;     gemm_core256(acc, p.A + ((long)half * MH + tm * 256) * DM, DM, p.Wt_in + ((long)l * NPAD + tn * 128) * 1024, 1024, 1024, sA, sW);
.LBB0_967:
	s_and_b32 s0, s44, 7
	s_mulk_i32 s0, 0xff
	s_lshr_b32 s1, s44, 3
	s_add_i32 s12, s0, s1
	s_mul_hi_i32 s0, s12, 0x88888889
	s_add_i32 s0, s0, s12
	s_lshr_b32 s1, s0, 31
	s_ashr_i32 s0, s0, 4
	s_add_i32 s28, s0, s1
	s_mul_i32 s0, s28, 30
	s_sub_i32 s12, s12, s0
	s_lshl_b32 s0, s28, 8
	s_ashr_i32 s1, s0, 31
	s_add_u32 s0, s0, s40
	s_addc_u32 s1, s1, s41
	s_lshl_b64 s[0:1], s[0:1], 11
	s_add_u32 s36, s58, s0
	s_addc_u32 s37, s59, s1
	s_lshl_b32 s0, s12, 7
	s_ashr_i32 s1, s0, 31
	s_add_u32 s38, s43, s0
	s_addc_u32 s39, s42, s1
	v_readlane_b32 s72, v252, 38
	s_waitcnt vmcnt(2)
	v_mov_b32 v4, v198
	s_lshl_b64 s[38:39], s[38:39], 11
	v_lshlrev_b32_e32 v0, 3, v4
	v_readlane_b32 s86, v252, 52
	v_ashrrev_i32_e32 v5, 3, v4
	v_and_b32_e32 v6, 56, v0
	v_readlane_b32 s87, v252, 53
	s_add_u32 s38, s86, s38
	v_lshl_or_b32 v196, v5, 10, v6
	v_mov_b32_e32 v197, v177
	s_addc_u32 s39, s87, s39
	v_lshlrev_b64 v[0:1], 1, v[196:197]
	v_lshl_add_u64 v[2:3], s[36:37], 0, v[0:1]
	v_lshl_add_u64 v[0:1], s[38:39], 0, v[0:1]
	v_add_u32_e32 v176, 0x8000, v196
	global_load_dwordx4 v[132:135], v[0:1], off
	v_lshlrev_b64 v[0:1], 1, v[176:177]
	global_load_dwordx4 v[128:131], v[2:3], off
	v_lshl_add_u64 v[2:3], s[36:37], 0, v[0:1]
	v_lshl_add_u64 v[0:1], s[38:39], 0, v[0:1]
	v_add_u32_e32 v176, 0x10000, v196
	global_load_dwordx4 v[140:143], v[0:1], off
	v_lshlrev_b64 v[0:1], 1, v[176:177]
	global_load_dwordx4 v[136:139], v[2:3], off
	v_lshl_add_u64 v[2:3], s[36:37], 0, v[0:1]
	v_lshl_add_u64 v[0:1], s[38:39], 0, v[0:1]
	v_add_u32_e32 v176, 0x18000, v196
	global_load_dwordx4 v[148:151], v[0:1], off
	v_lshlrev_b64 v[0:1], 1, v[176:177]
	global_load_dwordx4 v[144:147], v[2:3], off
	v_lshl_add_u64 v[2:3], s[36:37], 0, v[0:1]
	v_lshl_add_u64 v[0:1], s[38:39], 0, v[0:1]
	v_add_u32_e32 v176, 0x20000, v196
	global_load_dwordx4 v[156:159], v[0:1], off
	v_lshl_add_u64 v[0:1], v[176:177], 1, s[36:37]
	v_add_u32_e32 v176, 0x28000, v196
	global_load_dwordx4 v[152:155], v[2:3], off
	v_lshl_add_u64 v[2:3], v[176:177], 1, s[36:37]
	v_add_u32_e32 v176, 0x30000, v196
	global_load_dwordx4 v[164:167], v[0:1], off
	global_load_dwordx4 v[160:163], v[2:3], off
	v_lshl_add_u64 v[0:1], v[176:177], 1, s[36:37]
	v_add_u32_e32 v176, 0x38000, v196
	v_lshl_add_u64 v[2:3], v[176:177], 1, s[36:37]
	global_load_dwordx4 v[168:171], v[0:1], off
	global_load_dwordx4 v[172:175], v[2:3], off
	v_lshlrev_b32_e32 v0, 1, v6
	v_mul_lo_u32 v5, v5, s23
	v_and_b32_e32 v1, 0xfffff9f, v4
	v_lshrrev_b32_e32 v2, 1, v4
	v_and_b32_e32 v3, 0x5f, v4
	v_add_u32_e32 v221, v0, v5
	v_or_b32_e32 v0, 0x60, v4
	v_and_b32_e32 v2, 16, v2
	v_mul_lo_u32 v1, v1, s23
	v_mul_lo_u32 v4, v0, s23
	v_mul_u32_u24_e32 v3, 0x90, v3
	v_mov_b32_e32 v0, 0
	s_mov_b32 s13, 0
	v_add_u32_e32 v219, v2, v1
	v_add_u32_e32 v197, v2, v4
	v_add_u32_e32 v220, v2, v3
	v_mov_b32_e32 v1, v0
	v_mov_b32_e32 v2, v0
	v_mov_b32_e32 v3, v0
	v_mov_b32_e32 v4, v0
	v_mov_b32_e32 v5, v0
	v_mov_b32_e32 v6, v0
	v_mov_b32_e32 v7, v0
	s_waitcnt vmcnt(13)
	v_mov_b32_e32 v8, v0
	v_mov_b32_e32 v9, v0
	v_mov_b32_e32 v10, v0
	v_mov_b32_e32 v11, v0
	s_waitcnt vmcnt(12)
	v_mov_b32_e32 v12, v0
	v_mov_b32_e32 v13, v0
	v_mov_b32_e32 v14, v0
	v_mov_b32_e32 v15, v0
	v_mov_b32_e32 v16, v0
	v_mov_b32_e32 v17, v0
	v_mov_b32_e32 v18, v0
	v_mov_b32_e32 v19, v0
	v_mov_b32_e32 v20, v0
	v_mov_b32_e32 v21, v0
	v_mov_b32_e32 v22, v0
	v_mov_b32_e32 v23, v0
	v_mov_b32_e32 v24, v0
	v_mov_b32_e32 v25, v0
	v_mov_b32_e32 v26, v0
	v_mov_b32_e32 v27, v0
	v_mov_b32_e32 v28, v0
	v_mov_b32_e32 v29, v0
	v_mov_b32_e32 v30, v0
	v_mov_b32_e32 v31, v0
	v_mov_b32_e32 v32, v0
	v_mov_b32_e32 v33, v0
	v_mov_b32_e32 v34, v0
	v_mov_b32_e32 v35, v0
	v_mov_b32_e32 v36, v0
	v_mov_b32_e32 v37, v0
	v_mov_b32_e32 v38, v0
	v_mov_b32_e32 v39, v0
	v_mov_b32_e32 v40, v0
	v_mov_b32_e32 v41, v0
	v_mov_b32_e32 v42, v0
	v_mov_b32_e32 v43, v0
	v_mov_b32_e32 v44, v0
	v_mov_b32_e32 v45, v0
	v_mov_b32_e32 v46, v0
	v_mov_b32_e32 v47, v0
	v_mov_b32_e32 v48, v0
	v_mov_b32_e32 v49, v0
	v_mov_b32_e32 v50, v0
	v_mov_b32_e32 v51, v0
	v_mov_b32_e32 v52, v0
	v_mov_b32_e32 v53, v0
	v_mov_b32_e32 v54, v0
	v_mov_b32_e32 v55, v0
	v_mov_b32_e32 v56, v0
	v_mov_b32_e32 v57, v0
	v_mov_b32_e32 v58, v0
	v_mov_b32_e32 v59, v0
	v_mov_b32_e32 v60, v0
	v_mov_b32_e32 v61, v0
	v_mov_b32_e32 v62, v0
	v_mov_b32_e32 v63, v0
	v_mov_b32_e32 v64, v0
	v_mov_b32_e32 v65, v0
	v_mov_b32_e32 v66, v0
	v_mov_b32_e32 v67, v0
	v_mov_b32_e32 v68, v0
	v_mov_b32_e32 v69, v0
	v_mov_b32_e32 v70, v0
	v_mov_b32_e32 v71, v0
	v_mov_b32_e32 v72, v0
	v_mov_b32_e32 v73, v0
	v_mov_b32_e32 v74, v0
	v_mov_b32_e32 v75, v0
	v_mov_b32_e32 v76, v0
	v_mov_b32_e32 v77, v0
	v_mov_b32_e32 v78, v0
	v_mov_b32_e32 v79, v0
	v_mov_b32_e32 v80, v0
	v_mov_b32_e32 v81, v0
	v_mov_b32_e32 v82, v0
	v_mov_b32_e32 v83, v0
	v_mov_b32_e32 v84, v0
	v_mov_b32_e32 v85, v0
	v_mov_b32_e32 v86, v0
	v_mov_b32_e32 v87, v0
	v_mov_b32_e32 v88, v0
	v_mov_b32_e32 v89, v0
	v_mov_b32_e32 v90, v0
	v_mov_b32_e32 v91, v0
	v_mov_b32_e32 v92, v0
	v_mov_b32_e32 v93, v0
	v_mov_b32_e32 v94, v0
	v_mov_b32_e32 v95, v0
	v_mov_b32_e32 v96, v0
	v_mov_b32_e32 v97, v0
	v_mov_b32_e32 v98, v0
	v_mov_b32_e32 v99, v0
	v_mov_b32_e32 v100, v0
	v_mov_b32_e32 v101, v0
	v_mov_b32_e32 v102, v0
	v_mov_b32_e32 v103, v0
	v_mov_b32_e32 v104, v0
	v_mov_b32_e32 v105, v0
	v_mov_b32_e32 v106, v0
	v_mov_b32_e32 v107, v0
	v_mov_b32_e32 v108, v0
	v_mov_b32_e32 v109, v0
	v_mov_b32_e32 v110, v0
	v_mov_b32_e32 v111, v0
	v_mov_b32_e32 v112, v0
	v_mov_b32_e32 v113, v0
	v_mov_b32_e32 v114, v0
	v_mov_b32_e32 v115, v0
	v_mov_b32_e32 v116, v0
	v_mov_b32_e32 v117, v0
	v_mov_b32_e32 v118, v0
	v_mov_b32_e32 v119, v0
	v_mov_b32_e32 v120, v0
	v_mov_b32_e32 v121, v0
	v_mov_b32_e32 v122, v0
	v_mov_b32_e32 v123, v0
	v_mov_b32_e32 v124, v0
	v_mov_b32_e32 v125, v0
	v_mov_b32_e32 v126, v0
	v_mov_b32_e32 v127, v0
	v_readlane_b32 s73, v252, 39
	v_readlane_b32 s74, v252, 40
	v_readlane_b32 s75, v252, 41
	v_readlane_b32 s76, v252, 42
	v_readlane_b32 s77, v252, 43
	v_readlane_b32 s78, v252, 44
	v_readlane_b32 s79, v252, 45
	v_readlane_b32 s80, v252, 46
	v_readlane_b32 s81, v252, 47
	v_readlane_b32 s82, v252, 48
	v_readlane_b32 s83, v252, 49
	v_readlane_b32 s84, v252, 50
	v_readlane_b32 s85, v252, 51
